# P0 f32->bf16 copy stores carry the nt (streaming) hint like its loads
# speedup vs baseline: 1.0077x; 1.0048x over previous
; __device__ __forceinline__ u32x4 pack8(const f32x4 a, const f32x4 b) { u32x4 w; w.x = cvt_pk_bf16(a[0], a[1]); w.y = cvt_pk_bf16(a[2], a[3]); w.z = cvt_pk_bf16(b[0], b[1]); w.w = cvt_pk_bf16(b[2], b[3]); return w; }
; __device__ __forceinline__ void p0_prologue(const Params& p, const Frame& F0) {
;     ...
;         for (size_t i0 = gt; i0 < C_ALL; i0 += 4 * NT) {
;             f32x4 a[4], b[4]; bf16_t* dst[4]; bool ok[4];
; #pragma unroll
;             for (int q = 0; q < 4; ++q) {
;                 const size_t i = i0 + q * NT; ok[q] = i < C_ALL; const size_t ic = ok[q] ? i : gt; const float* src;
;                 if (ic < C_X) { src = (ic < C_XP) ? p.in[0] + ic * 8 : p.in[1] + (ic - C_XP) * 8; dst[q] = Xb + ic * 8; }
;                 else if (ic < C_X + C_K) { const size_t k = ic - C_X; src = p.in[5] + k * 8; dst[q] = Kb + (size_t)NB * NMEM * DM + k * 8; }
;                 else { const size_t k = ic - C_X - C_K; src = p.in[7] + k * 8; dst[q] = Mb + k * 8; }
;                 a[q] = __builtin_nontemporal_load((const f32x4*)src); b[q] = __builtin_nontemporal_load((const f32x4*)(src + 4));
;             }
; #pragma unroll
;             for (int q = 0; q < 4; ++q) if (ok[q]) *(u32x4*)dst[q] = pg8::pack8(a[q], b[q]);
;         }
.LBB0_191:
	s_or_b64 exec, exec, s[26:27]
	s_waitcnt vmcnt(7)
	global_load_dwordx4 v[26:29], v[30:31], off offset:16 nt
	s_nop 0
	global_load_dwordx4 v[30:33], v[30:31], off nt
	s_waitcnt vmcnt(6)
	v_cvt_pk_bf16_f32 v6, v6, v7
	v_cvt_pk_bf16_f32 v7, v8, v9
	v_cvt_pk_bf16_f32 v8, v2, v3
	v_cvt_pk_bf16_f32 v9, v4, v5
	global_store_dwordx4 v[44:45], v[6:9], off nt
	s_and_saveexec_b64 s[6:7], vcc
	s_cbranch_execz .LBB0_194
	s_waitcnt vmcnt(5)
	v_cvt_pk_bf16_f32 v2, v14, v15
	v_cvt_pk_bf16_f32 v3, v16, v17
	v_cvt_pk_bf16_f32 v4, v10, v11
	v_cvt_pk_bf16_f32 v5, v12, v13
	global_store_dwordx4 v[46:47], v[2:5], off nt
	s_or_b64 exec, exec, s[6:7]
	s_and_saveexec_b64 s[6:7], s[0:1]
	s_cbranch_execnz .LBB0_195

; __device__ __forceinline__ u32x4 pack8(const f32x4 a, const f32x4 b) { u32x4 w; w.x = cvt_pk_bf16(a[0], a[1]); w.y = cvt_pk_bf16(a[2], a[3]); w.z = cvt_pk_bf16(b[0], b[1]); w.w = cvt_pk_bf16(b[2], b[3]); return w; }
; __device__ __forceinline__ void p0_prologue(const Params& p, const Frame& F0) {
;     ...
; #pragma unroll
;             for (int q = 0; q < 4; ++q) if (ok[q]) *(u32x4*)dst[q] = pg8::pack8(a[q], b[q]);
;         }
.LBB0_195:
	s_waitcnt vmcnt(3)
	v_cvt_pk_bf16_f32 v2, v22, v23
	v_cvt_pk_bf16_f32 v3, v24, v25
	v_cvt_pk_bf16_f32 v4, v18, v19
	v_cvt_pk_bf16_f32 v5, v20, v21
	global_store_dwordx4 v[48:49], v[2:5], off nt
	s_or_b64 exec, exec, s[6:7]
	s_and_saveexec_b64 s[0:1], s[4:5]
	s_cbranch_execz .LBB0_158
.LBB0_196:
	s_waitcnt vmcnt(1)
	v_cvt_pk_bf16_f32 v2, v30, v31
	v_cvt_pk_bf16_f32 v3, v32, v33
	v_cvt_pk_bf16_f32 v4, v26, v27
	v_cvt_pk_bf16_f32 v5, v28, v29
	global_store_dwordx4 v[50:51], v[2:5], off nt
	s_branch .LBB0_158
